# short conv outputs written with non-temporal stores
# speedup vs baseline: 1.0339x; 1.0015x over previous
; __device__ __forceinline__ int fresh_tid() { int t = threadIdx.x; asm volatile("" : "+v"(t)); return t; }
; __device__ void conv_naive(const Params& p, int l, const bf16_t* proj, bf16_t* ycat) {
;     for (int gidx = blockIdx.x * NTHREADS + fresh_tid(); gidx < (SEQ / 8) * 128; gidx += gridDim.x * NTHREADS) {
;         const int tb = (gidx >> 7) * 8, c = (gidx & 127) * 4;
;         u32x2 hh[10], cc[10], bb[8];
; #pragma unroll
;         for (int j = 0; j < 10; ++j) { const int ts = tb + j - 1; const bool ok = ts >= 0 && ts < SEQ; const int tc = ok ? ts : tb;
;             hh[j] = *(const u32x2*)(proj + (size_t)tc * NP + CH + c); cc[j] = *(const u32x2*)(proj + (size_t)tc * NP + CC + c);
;             if (!ok) { hh[j].x = 0u; hh[j].y = 0u; } }
; #pragma unroll
;         for (int j = 0; j < 8; ++j) bb[j] = *(const u32x2*)(proj + (size_t)(tb + j) * NP + CB + c);
.LBB0_482:
	v_ashrrev_i32_e32 v52, 4, v54
	v_and_b32_e32 v0, -8, v52
	v_add_u32_e32 v1, -1, v0
	v_cmp_gt_u32_e64 s[4:5], s22, v1
	v_and_b32_e32 v53, 0x1fc, v55
	v_mov_b64_e32 v[14:15], s[94:95]
	v_cndmask_b32_e64 v1, v0, v1, s[4:5]
	v_mad_i64_i32 v[2:3], s[12:13], v1, s63, v[14:15]
	v_lshlrev_b32_e32 v188, 1, v53
	v_lshl_add_u64 v[2:3], v[2:3], 0, v[188:189]
	v_add_co_u32_e32 v4, vcc, 0x1000, v2
	v_or_b32_e32 v10, 2, v0
	s_nop 0
	v_addc_co_u32_e32 v5, vcc, 0, v3, vcc
	global_load_dwordx2 v[120:121], v[4:5], off offset:3584
	v_add_co_u32_e32 v2, vcc, 0x2000, v2
	v_or_b32_e32 v8, 3, v0
	s_nop 0
	v_addc_co_u32_e32 v3, vcc, 0, v3, vcc
	global_load_dwordx2 v[24:25], v[2:3], off offset:1536
	v_mad_i64_i32 v[2:3], s[12:13], v0, s63, v[14:15]
	v_lshl_add_u64 v[2:3], v[2:3], 0, v[188:189]
	v_or_b32_e32 v6, 4, v0
	v_or_b32_e32 v28, 1, v0
	v_ashrrev_i32_e32 v1, 31, v0
	v_ashrrev_i32_e32 v29, 31, v28
	v_ashrrev_i32_e32 v11, 31, v10
	v_ashrrev_i32_e32 v9, 31, v8
	v_ashrrev_i32_e32 v7, 31, v6
	v_add_u32_e32 v54, s18, v54
	v_add_u32_e32 v55, s19, v55
	v_cndmask_b32_e64 v140, 0, 1, s[4:5]
	v_add_co_u32_e32 v4, vcc, s66, v2
	s_nop 0
	v_addc_co_u32_e32 v5, vcc, 0, v3, vcc
	global_load_dwordx2 v[122:123], v[4:5], off offset:3584
	v_cmp_gt_u32_e64 s[4:5], s22, v52
	v_add_co_u32_e32 v12, vcc, s92, v2
	s_nop 0
	v_cndmask_b32_e64 v2, 0, 1, s[4:5]
	v_cndmask_b32_e64 v141, 0, 1, s[4:5]
	v_or_b32_e32 v2, v0, v2
	v_addc_co_u32_e32 v13, vcc, 0, v3, vcc
	v_mad_i64_i32 v[2:3], s[12:13], v2, s63, v[14:15]
	v_lshl_add_u64 v[2:3], v[2:3], 0, v[188:189]
	global_load_dwordx2 v[30:31], v[12:13], off offset:1536
	global_load_dwordx2 v[44:45], v[12:13], off offset:512
	v_add_co_u32_e32 v4, vcc, s66, v2
	s_nop 0
	v_addc_co_u32_e32 v5, vcc, 0, v3, vcc
	global_load_dwordx2 v[124:125], v[4:5], off offset:3584
	v_add_co_u32_e32 v2, vcc, s92, v2
	s_nop 0
	v_addc_co_u32_e32 v3, vcc, 0, v3, vcc
	global_load_dwordx2 v[32:33], v[2:3], off offset:1536
	v_cndmask_b32_e64 v2, v0, v10, s[4:5]
	v_mad_i64_i32 v[2:3], s[12:13], v2, s63, v[14:15]
	v_lshl_add_u64 v[2:3], v[2:3], 0, v[188:189]
	v_add_co_u32_e32 v4, vcc, s66, v2
	s_nop 0
	v_addc_co_u32_e32 v5, vcc, 0, v3, vcc
	global_load_dwordx2 v[126:127], v[4:5], off offset:3584
	v_add_co_u32_e32 v2, vcc, s92, v2
	s_nop 1
	v_addc_co_u32_e32 v3, vcc, 0, v3, vcc
	global_load_dwordx2 v[34:35], v[2:3], off offset:1536
	v_cndmask_b32_e64 v2, v0, v8, s[4:5]
	v_mad_i64_i32 v[2:3], s[12:13], v2, s63, v[14:15]
	v_lshl_add_u64 v[2:3], v[2:3], 0, v[188:189]
	v_add_co_u32_e32 v4, vcc, s66, v2
	s_nop 0
	v_addc_co_u32_e32 v5, vcc, 0, v3, vcc
	global_load_dwordx2 v[128:129], v[4:5], off offset:3584
	v_add_co_u32_e32 v2, vcc, s92, v2
	s_nop 1
	v_addc_co_u32_e32 v3, vcc, 0, v3, vcc
	global_load_dwordx2 v[38:39], v[2:3], off offset:1536
	v_cndmask_b32_e64 v2, v0, v6, s[4:5]
	v_mad_i64_i32 v[2:3], s[12:13], v2, s63, v[14:15]
	v_lshl_add_u64 v[2:3], v[2:3], 0, v[188:189]
	v_add_co_u32_e32 v4, vcc, s66, v2
	s_nop 0
	v_addc_co_u32_e32 v5, vcc, 0, v3, vcc
	global_load_dwordx2 v[130:131], v[4:5], off offset:3584
	v_add_co_u32_e32 v2, vcc, s92, v2
	s_nop 1
	v_addc_co_u32_e32 v3, vcc, 0, v3, vcc
	global_load_dwordx2 v[40:41], v[2:3], off offset:1536
	v_or_b32_e32 v4, 5, v0
	v_cndmask_b32_e64 v2, v0, v4, s[4:5]
	v_mad_i64_i32 v[2:3], s[12:13], v2, s63, v[14:15]
	v_lshl_add_u64 v[2:3], v[2:3], 0, v[188:189]
	v_add_co_u32_e32 v16, vcc, s66, v2
	s_nop 0
	v_addc_co_u32_e32 v17, vcc, 0, v3, vcc
	global_load_dwordx2 v[132:133], v[16:17], off offset:3584
	v_add_co_u32_e32 v2, vcc, s92, v2
	v_ashrrev_i32_e32 v5, 31, v4
	s_nop 0
	v_addc_co_u32_e32 v3, vcc, 0, v3, vcc
	global_load_dwordx2 v[42:43], v[2:3], off offset:1536
	v_or_b32_e32 v2, 6, v0
	v_cndmask_b32_e64 v3, v0, v2, s[4:5]
	v_mad_i64_i32 v[16:17], s[12:13], v3, s63, v[14:15]
	v_lshl_add_u64 v[16:17], v[16:17], 0, v[188:189]
	v_add_co_u32_e32 v18, vcc, s66, v16
	v_cndmask_b32_e64 v3, 0, 7, s[4:5]
	s_nop 0
	v_addc_co_u32_e32 v19, vcc, 0, v17, vcc
	global_load_dwordx2 v[134:135], v[18:19], off offset:3584
	v_add_co_u32_e32 v16, vcc, s92, v16
	v_or_b32_e32 v3, v3, v0
	s_nop 0
	v_addc_co_u32_e32 v17, vcc, 0, v17, vcc
	global_load_dwordx2 v[46:47], v[16:17], off offset:1536
	v_mad_i64_i32 v[16:17], s[12:13], v3, s63, v[14:15]
	v_lshl_add_u64 v[16:17], v[16:17], 0, v[188:189]
	v_add_u32_e32 v3, 8, v0
	v_add_co_u32_e32 v18, vcc, s66, v16
	s_nop 0
	v_addc_co_u32_e32 v19, vcc, 0, v17, vcc
	global_load_dwordx2 v[136:137], v[18:19], off offset:3584
	v_add_co_u32_e32 v16, vcc, s92, v16
	s_nop 1
	v_addc_co_u32_e32 v17, vcc, 0, v17, vcc
	global_load_dwordx2 v[48:49], v[16:17], off offset:1536
	v_cmp_gt_u32_e64 s[4:5], s22, v3
	s_nop 1
	v_cndmask_b32_e64 v3, v0, v3, s[4:5]
	v_cndmask_b32_e64 v142, 0, 1, s[4:5]
	v_mad_i64_i32 v[16:17], s[12:13], v3, s63, v[14:15]
	v_lshl_add_u64 v[16:17], v[16:17], 0, v[188:189]
	v_add_co_u32_e32 v18, vcc, s66, v16
	v_lshlrev_b64 v[0:1], 10, v[0:1]
	s_nop 0
	v_addc_co_u32_e32 v19, vcc, 0, v17, vcc
	global_load_dwordx2 v[138:139], v[18:19], off offset:3584
	v_add_co_u32_e32 v16, vcc, s92, v16
	v_ashrrev_i32_e32 v3, 31, v2
	s_nop 0
	v_addc_co_u32_e32 v17, vcc, 0, v17, vcc
	global_load_dwordx2 v[50:51], v[16:17], off offset:1536
	v_mad_i64_i32 v[12:13], s[4:5], v28, s63, v[14:15]
	v_lshl_add_u64 v[12:13], v[12:13], 0, v[188:189]
	v_add_co_u32_e32 v12, vcc, s92, v12
	s_nop 1
	v_addc_co_u32_e32 v13, vcc, 0, v13, vcc
	global_load_dwordx2 v[36:37], v[12:13], off offset:512
	v_mad_i64_i32 v[12:13], s[4:5], v10, s63, v[14:15]
	v_lshl_add_u64 v[12:13], v[12:13], 0, v[188:189]
	v_add_co_u32_e32 v12, vcc, s92, v12
	s_nop 1
	v_addc_co_u32_e32 v13, vcc, 0, v13, vcc
	global_load_dwordx2 v[26:27], v[12:13], off offset:512
; __device__ __forceinline__ float bf_lo(unsigned w) { return __uint_as_float(w << 16); }
; __device__ __forceinline__ float bf_hi(unsigned w) { return __uint_as_float(w & 0xffff0000u); }
; __device__ void conv_naive(const Params& p, int l, const bf16_t* proj, bf16_t* ycat) {
;     ...
;         for (int j = 0; j < 10; ++j) { const int ts = tb + j - 1; const bool ok = ts >= 0 && ts < SEQ; const int tc = ok ? ts : tb;
;             hh[j] = *(const u32x2*)(proj + (size_t)tc * NP + CH + c); cc[j] = *(const u32x2*)(proj + (size_t)tc * NP + CC + c);
;             if (!ok) { hh[j].x = 0u; hh[j].y = 0u; } }
; #pragma unroll
;         for (int j = 0; j < 8; ++j) bb[j] = *(const u32x2*)(proj + (size_t)(tb + j) * NP + CB + c);
;         f32x4 w[3];
; #pragma unroll
;         for (int j = 0; j < 3; ++j) w[j] = *(const f32x4*)(p.conv_w + ((size_t)l * 3 + j) * 512 + c);
;         f32x4 u[10];
; #pragma unroll
;         for (int j = 0; j < 10; ++j) { u[j][0] = bf_lo(hh[j].x) * bf_lo(cc[j].x); u[j][1] = bf_hi(hh[j].x) * bf_hi(cc[j].x); u[j][2] = bf_lo(hh[j].y) * bf_lo(cc[j].y); u[j][3] = bf_hi(hh[j].y) * bf_hi(cc[j].y); }
	v_mad_i64_i32 v[12:13], s[4:5], v8, s63, v[14:15]
	v_lshl_add_u64 v[12:13], v[12:13], 0, v[188:189]
	v_add_co_u32_e32 v12, vcc, s92, v12
	s_nop 1
	v_addc_co_u32_e32 v13, vcc, 0, v13, vcc
	global_load_dwordx2 v[22:23], v[12:13], off offset:512
	v_mad_i64_i32 v[12:13], s[4:5], v6, s63, v[14:15]
	v_lshl_add_u64 v[12:13], v[12:13], 0, v[188:189]
	v_add_co_u32_e32 v12, vcc, s92, v12
	s_nop 1
	v_addc_co_u32_e32 v13, vcc, 0, v13, vcc
	global_load_dwordx2 v[20:21], v[12:13], off offset:512
	v_mad_i64_i32 v[12:13], s[4:5], v4, s63, v[14:15]
	v_lshl_add_u64 v[12:13], v[12:13], 0, v[188:189]
	v_add_co_u32_e32 v12, vcc, s92, v12
	s_nop 1
	v_addc_co_u32_e32 v13, vcc, 0, v13, vcc
	global_load_dwordx2 v[18:19], v[12:13], off offset:512
	v_mad_i64_i32 v[12:13], s[4:5], v2, s63, v[14:15]
	v_lshl_add_u64 v[12:13], v[12:13], 0, v[188:189]
	v_add_co_u32_e32 v12, vcc, s92, v12
	s_nop 1
	v_addc_co_u32_e32 v13, vcc, 0, v13, vcc
	global_load_dwordx2 v[16:17], v[12:13], off offset:512
	v_or_b32_e32 v12, 7, v52
	v_mad_i64_i32 v[14:15], s[4:5], v12, s63, v[14:15]
	v_lshl_add_u64 v[14:15], v[14:15], 0, v[188:189]
	v_add_co_u32_e32 v14, vcc, s92, v14
	v_lshlrev_b32_e32 v52, 2, v53
	v_mov_b32_e32 v53, v189
	v_addc_co_u32_e32 v15, vcc, 0, v15, vcc
	v_lshl_add_u64 v[84:85], s[8:9], 0, v[52:53]
	global_load_dwordx2 v[14:15], v[14:15], off offset:512
	s_nop 0
	global_load_dwordx4 v[76:79], v52, s[8:9]
	global_load_dwordx4 v[80:83], v52, s[8:9] offset:2048
	v_add_co_u32_e32 v52, vcc, s66, v84
	v_ashrrev_i32_e32 v13, 31, v12
	s_nop 0
	v_addc_co_u32_e32 v53, vcc, 0, v85, vcc
	global_load_dwordx4 v[84:87], v[52:53], off
	s_waitcnt vmcnt(10)
	v_cmp_ne_u32_e32 vcc, 0, v142
	s_nop 1
	v_cndmask_b32_e32 v73, 0, v139, vcc
	v_cndmask_b32_e32 v75, 0, v138, vcc
	v_cmp_ne_u32_e32 vcc, 0, v140
	s_nop 1
	v_cndmask_b32_e32 v58, 0, v120, vcc
	v_cndmask_b32_e32 v56, 0, v121, vcc
	v_cmp_ne_u32_e32 vcc, 0, v141
	s_nop 1
	v_cndmask_b32_e32 v60, 0, v122, vcc
	v_cndmask_b32_e32 v57, 0, v123, vcc
	v_cndmask_b32_e32 v62, 0, v124, vcc
	v_cndmask_b32_e32 v59, 0, v125, vcc
	v_cndmask_b32_e32 v64, 0, v126, vcc
	v_cndmask_b32_e32 v61, 0, v127, vcc
	v_cndmask_b32_e32 v66, 0, v128, vcc
	v_cndmask_b32_e32 v63, 0, v129, vcc
	v_cndmask_b32_e32 v68, 0, v130, vcc
	v_cndmask_b32_e32 v65, 0, v131, vcc
	v_cndmask_b32_e32 v67, 0, v133, vcc
	v_cndmask_b32_e32 v70, 0, v132, vcc
	v_cndmask_b32_e32 v72, 0, v134, vcc
	v_cndmask_b32_e32 v69, 0, v135, vcc
	v_cndmask_b32_e32 v71, 0, v137, vcc
	v_cndmask_b32_e32 v74, 0, v136, vcc
	v_lshlrev_b32_e32 v88, 16, v24
	v_and_b32_e32 v89, 0xffff0000, v24
	v_lshlrev_b32_e32 v24, 16, v25
	v_and_b32_e32 v25, 0xffff0000, v25
	v_lshlrev_b32_e32 v90, 16, v30
	v_and_b32_e32 v91, 0xffff0000, v30
	v_lshlrev_b32_e32 v30, 16, v31
	v_and_b32_e32 v31, 0xffff0000, v31
	v_lshlrev_b32_e32 v52, 16, v58
	v_and_b32_e32 v53, 0xffff0000, v58
	v_pk_mul_f32 v[52:53], v[88:89], v[52:53]
	v_lshlrev_b32_e32 v88, 16, v56
	v_and_b32_e32 v89, 0xffff0000, v56
	v_pk_mul_f32 v[24:25], v[24:25], v[88:89]
	v_lshlrev_b32_e32 v88, 16, v60
	v_and_b32_e32 v89, 0xffff0000, v60
	v_lshlrev_b32_e32 v56, 16, v57
	v_and_b32_e32 v57, 0xffff0000, v57
	v_pk_mul_f32 v[88:89], v[88:89], v[90:91]
	v_pk_mul_f32 v[30:31], v[56:57], v[30:31]
	v_lshlrev_b32_e32 v56, 16, v62
	v_and_b32_e32 v57, 0xffff0000, v62
	v_lshlrev_b32_e32 v90, 16, v32
	v_and_b32_e32 v91, 0xffff0000, v32
	v_lshlrev_b32_e32 v58, 16, v59
	v_and_b32_e32 v59, 0xffff0000, v59
	v_lshlrev_b32_e32 v32, 16, v33
	v_and_b32_e32 v33, 0xffff0000, v33
	v_pk_mul_f32 v[56:57], v[56:57], v[90:91]
	v_pk_mul_f32 v[32:33], v[58:59], v[32:33]
	v_lshlrev_b32_e32 v58, 16, v64
	v_and_b32_e32 v59, 0xffff0000, v64
	v_lshlrev_b32_e32 v90, 16, v34
	v_and_b32_e32 v91, 0xffff0000, v34
	v_lshlrev_b32_e32 v60, 16, v61
	v_and_b32_e32 v61, 0xffff0000, v61
	v_lshlrev_b32_e32 v34, 16, v35
	v_and_b32_e32 v35, 0xffff0000, v35
	v_pk_mul_f32 v[58:59], v[58:59], v[90:91]
	v_pk_mul_f32 v[34:35], v[60:61], v[34:35]
	v_lshlrev_b32_e32 v60, 16, v66
	v_and_b32_e32 v61, 0xffff0000, v66
	v_lshlrev_b32_e32 v90, 16, v38
	v_and_b32_e32 v91, 0xffff0000, v38
	v_lshlrev_b32_e32 v62, 16, v63
	v_and_b32_e32 v63, 0xffff0000, v63
	v_lshlrev_b32_e32 v38, 16, v39
	v_and_b32_e32 v39, 0xffff0000, v39
	v_pk_mul_f32 v[60:61], v[60:61], v[90:91]
	v_pk_mul_f32 v[38:39], v[62:63], v[38:39]
	v_lshlrev_b32_e32 v62, 16, v68
	v_and_b32_e32 v63, 0xffff0000, v68
	v_lshlrev_b32_e32 v90, 16, v40
	v_and_b32_e32 v91, 0xffff0000, v40
	v_lshlrev_b32_e32 v64, 16, v65
	v_and_b32_e32 v65, 0xffff0000, v65
	v_lshlrev_b32_e32 v40, 16, v41
	v_and_b32_e32 v41, 0xffff0000, v41
	v_pk_mul_f32 v[62:63], v[62:63], v[90:91]
	v_pk_mul_f32 v[40:41], v[64:65], v[40:41]
	v_lshlrev_b32_e32 v64, 16, v70
	v_and_b32_e32 v65, 0xffff0000, v70
	v_lshlrev_b32_e32 v90, 16, v42
	v_and_b32_e32 v91, 0xffff0000, v42
	v_lshlrev_b32_e32 v66, 16, v67
	v_and_b32_e32 v67, 0xffff0000, v67
	v_lshlrev_b32_e32 v42, 16, v43
	v_and_b32_e32 v43, 0xffff0000, v43
	v_pk_mul_f32 v[64:65], v[64:65], v[90:91]
	v_pk_mul_f32 v[42:43], v[66:67], v[42:43]
	v_lshlrev_b32_e32 v66, 16, v72
	v_and_b32_e32 v67, 0xffff0000, v72
	v_lshlrev_b32_e32 v90, 16, v46
	v_and_b32_e32 v91, 0xffff0000, v46
	v_lshlrev_b32_e32 v68, 16, v69
	v_and_b32_e32 v69, 0xffff0000, v69
	v_lshlrev_b32_e32 v46, 16, v47
	v_and_b32_e32 v47, 0xffff0000, v47
	v_pk_mul_f32 v[66:67], v[66:67], v[90:91]
	v_pk_mul_f32 v[46:47], v[68:69], v[46:47]
	v_lshlrev_b32_e32 v68, 16, v74
	v_and_b32_e32 v69, 0xffff0000, v74
	v_lshlrev_b32_e32 v90, 16, v48
	v_and_b32_e32 v91, 0xffff0000, v48
	v_lshlrev_b32_e32 v70, 16, v71
	v_and_b32_e32 v71, 0xffff0000, v71
	v_lshlrev_b32_e32 v48, 16, v49
	v_and_b32_e32 v49, 0xffff0000, v49
	v_pk_mul_f32 v[68:69], v[68:69], v[90:91]
	v_pk_mul_f32 v[48:49], v[70:71], v[48:49]
	v_lshlrev_b32_e32 v70, 16, v75
	v_and_b32_e32 v71, 0xffff0000, v75
	v_lshlrev_b32_e32 v74, 16, v50
	v_and_b32_e32 v75, 0xffff0000, v50
	s_waitcnt vmcnt(0)
; __device__ __forceinline__ unsigned cvt_pk_bf16(float lo, float hi) { unsigned r; asm("v_cvt_pk_bf16_f32 %0, %1, %2" : "=v"(r) : "v"(lo), "v"(hi)); return r; }
; __device__ __forceinline__ float bf_lo(unsigned w) { return __uint_as_float(w << 16); }
; __device__ __forceinline__ float bf_hi(unsigned w) { return __uint_as_float(w & 0xffff0000u); }
; __device__ void conv_naive(const Params& p, int l, const bf16_t* proj, bf16_t* ycat) {
;     ...
;         for (int j = 0; j < 10; ++j) { u[j][0] = bf_lo(hh[j].x) * bf_lo(cc[j].x); u[j][1] = bf_hi(hh[j].x) * bf_hi(cc[j].x); u[j][2] = bf_lo(hh[j].y) * bf_lo(cc[j].y); u[j][3] = bf_hi(hh[j].y) * bf_hi(cc[j].y); }
; #pragma unroll
;         for (int j = 0; j < 8; ++j) { const f32x4 a = w[0] * u[j] + w[1] * u[j + 1] + w[2] * u[j + 2];
;             u32x2 o; o.x = cvt_pk_bf16(a[0] * bf_lo(bb[j].x), a[1] * bf_hi(bb[j].x)); o.y = cvt_pk_bf16(a[2] * bf_lo(bb[j].y), a[3] * bf_hi(bb[j].y));
;             *(u32x2*)(ycat + (size_t)SEQ * 512 + (size_t)(tb + j) * 512 + c) = o; }
;     }
	v_pk_mul_f32 v[90:91], v[88:89], v[80:81]
	v_pk_mul_f32 v[70:71], v[70:71], v[74:75]
	v_pk_mul_f32 v[74:75], v[30:31], v[82:83]
	v_pk_fma_f32 v[52:53], v[52:53], v[76:77], v[90:91]
	v_pk_fma_f32 v[24:25], v[24:25], v[78:79], v[74:75]
	v_pk_fma_f32 v[52:53], v[56:57], v[84:85], v[52:53]
	v_lshlrev_b32_e32 v74, 16, v44
	v_and_b32_e32 v44, 0xffff0000, v44
	v_mul_f32_e32 v52, v52, v74
	v_mul_f32_e32 v44, v53, v44
	v_lshlrev_b32_e32 v72, 16, v73
	v_and_b32_e32 v73, 0xffff0000, v73
	v_lshlrev_b32_e32 v50, 16, v51
	v_and_b32_e32 v51, 0xffff0000, v51
	v_pk_fma_f32 v[24:25], v[32:33], v[86:87], v[24:25]
	v_cvt_pk_bf16_f32 v44, v52, v44
	v_lshlrev_b32_e32 v52, 16, v45
	v_and_b32_e32 v45, 0xffff0000, v45
	v_pk_mul_f32 v[50:51], v[72:73], v[50:51]
	v_lshl_add_u64 v[72:73], s[20:21], 0, v[188:189]
	v_mul_f32_e32 v24, v24, v52
	v_mul_f32_e32 v25, v25, v45
	v_cvt_pk_bf16_f32 v45, v24, v25
	v_lshl_add_u64 v[0:1], v[72:73], 0, v[0:1]
	v_pk_mul_f32 v[24:25], v[56:57], v[80:81]
	global_store_dwordx2 v[0:1], v[44:45], off nt
	v_pk_mul_f32 v[0:1], v[32:33], v[82:83]
	v_pk_fma_f32 v[24:25], v[88:89], v[76:77], v[24:25]
	v_pk_fma_f32 v[0:1], v[30:31], v[78:79], v[0:1]
	v_pk_fma_f32 v[24:25], v[58:59], v[84:85], v[24:25]
	v_lshlrev_b32_e32 v30, 16, v36
	v_mul_f32_e32 v24, v24, v30
	v_and_b32_e32 v30, 0xffff0000, v36
	v_mul_f32_e32 v25, v25, v30
	v_pk_fma_f32 v[0:1], v[34:35], v[86:87], v[0:1]
	v_cvt_pk_bf16_f32 v24, v24, v25
	v_lshlrev_b32_e32 v25, 16, v37
	v_mul_f32_e32 v0, v0, v25
	v_and_b32_e32 v25, 0xffff0000, v37
	v_mul_f32_e32 v1, v1, v25
	v_cvt_pk_bf16_f32 v25, v0, v1
	v_lshlrev_b64 v[0:1], 10, v[28:29]
	v_lshl_add_u64 v[0:1], v[72:73], 0, v[0:1]
	global_store_dwordx2 v[0:1], v[24:25], off nt
	v_pk_mul_f32 v[24:25], v[58:59], v[80:81]
	v_pk_mul_f32 v[0:1], v[34:35], v[82:83]
	v_pk_fma_f32 v[24:25], v[56:57], v[76:77], v[24:25]
	v_lshlrev_b32_e32 v28, 16, v26
	v_pk_fma_f32 v[24:25], v[60:61], v[84:85], v[24:25]
	v_and_b32_e32 v26, 0xffff0000, v26
	v_pk_fma_f32 v[0:1], v[32:33], v[78:79], v[0:1]
	v_mul_f32_e32 v24, v24, v28
	v_mul_f32_e32 v25, v25, v26
	v_pk_fma_f32 v[0:1], v[38:39], v[86:87], v[0:1]
	v_cvt_pk_bf16_f32 v24, v24, v25
	v_lshlrev_b32_e32 v25, 16, v27
	v_mul_f32_e32 v0, v0, v25
	v_and_b32_e32 v25, 0xffff0000, v27
	v_mul_f32_e32 v1, v1, v25
	v_cvt_pk_bf16_f32 v25, v0, v1
	v_lshlrev_b64 v[0:1], 10, v[10:11]
	v_pk_mul_f32 v[10:11], v[60:61], v[80:81]
	v_lshl_add_u64 v[0:1], v[72:73], 0, v[0:1]
	v_pk_fma_f32 v[10:11], v[58:59], v[76:77], v[10:11]
	global_store_dwordx2 v[0:1], v[24:25], off nt
	v_pk_mul_f32 v[0:1], v[38:39], v[82:83]
	v_pk_fma_f32 v[10:11], v[62:63], v[84:85], v[10:11]
	v_lshlrev_b32_e32 v24, 16, v22
	v_and_b32_e32 v22, 0xffff0000, v22
	v_pk_fma_f32 v[0:1], v[34:35], v[78:79], v[0:1]
	v_mul_f32_e32 v10, v10, v24
	v_mul_f32_e32 v11, v11, v22
	v_pk_fma_f32 v[0:1], v[40:41], v[86:87], v[0:1]
	v_cvt_pk_bf16_f32 v10, v10, v11
	v_lshlrev_b32_e32 v11, 16, v23
	v_mul_f32_e32 v0, v0, v11
	v_and_b32_e32 v11, 0xffff0000, v23
	v_mul_f32_e32 v1, v1, v11
	v_cvt_pk_bf16_f32 v11, v0, v1
	v_lshlrev_b64 v[0:1], 10, v[8:9]
	v_pk_mul_f32 v[8:9], v[62:63], v[80:81]
	v_lshl_add_u64 v[0:1], v[72:73], 0, v[0:1]
	v_pk_fma_f32 v[8:9], v[60:61], v[76:77], v[8:9]
	global_store_dwordx2 v[0:1], v[10:11], off nt
	v_pk_fma_f32 v[8:9], v[64:65], v[84:85], v[8:9]
	v_lshlrev_b32_e32 v10, 16, v20
	v_pk_mul_f32 v[0:1], v[40:41], v[82:83]
	v_mul_f32_e32 v8, v8, v10
	v_and_b32_e32 v10, 0xffff0000, v20
	v_pk_fma_f32 v[0:1], v[38:39], v[78:79], v[0:1]
	v_mul_f32_e32 v9, v9, v10
	v_pk_fma_f32 v[0:1], v[42:43], v[86:87], v[0:1]
	v_cvt_pk_bf16_f32 v8, v8, v9
	v_lshlrev_b32_e32 v9, 16, v21
	v_mul_f32_e32 v0, v0, v9
	v_and_b32_e32 v9, 0xffff0000, v21
	v_mul_f32_e32 v1, v1, v9
	v_cvt_pk_bf16_f32 v9, v0, v1
	v_lshlrev_b64 v[0:1], 10, v[6:7]
	v_pk_mul_f32 v[6:7], v[64:65], v[80:81]
	v_lshl_add_u64 v[0:1], v[72:73], 0, v[0:1]
	v_pk_fma_f32 v[6:7], v[62:63], v[76:77], v[6:7]
	global_store_dwordx2 v[0:1], v[8:9], off nt
	v_pk_fma_f32 v[6:7], v[66:67], v[84:85], v[6:7]
	v_lshlrev_b32_e32 v8, 16, v18
	v_pk_mul_f32 v[0:1], v[42:43], v[82:83]
	v_mul_f32_e32 v6, v6, v8
	v_and_b32_e32 v8, 0xffff0000, v18
	v_pk_fma_f32 v[0:1], v[40:41], v[78:79], v[0:1]
	v_mul_f32_e32 v7, v7, v8
	v_pk_fma_f32 v[0:1], v[46:47], v[86:87], v[0:1]
	v_cvt_pk_bf16_f32 v6, v6, v7
	v_lshlrev_b32_e32 v7, 16, v19
	v_mul_f32_e32 v0, v0, v7
	v_and_b32_e32 v7, 0xffff0000, v19
	v_mul_f32_e32 v1, v1, v7
	v_cvt_pk_bf16_f32 v7, v0, v1
	v_lshlrev_b64 v[0:1], 10, v[4:5]
	v_pk_mul_f32 v[4:5], v[66:67], v[80:81]
	v_lshl_add_u64 v[0:1], v[72:73], 0, v[0:1]
	v_pk_fma_f32 v[4:5], v[64:65], v[76:77], v[4:5]
	global_store_dwordx2 v[0:1], v[6:7], off nt
	v_pk_fma_f32 v[4:5], v[68:69], v[84:85], v[4:5]
	v_lshlrev_b32_e32 v6, 16, v16
	v_pk_mul_f32 v[0:1], v[46:47], v[82:83]
	v_mul_f32_e32 v4, v4, v6
	v_and_b32_e32 v6, 0xffff0000, v16
	v_pk_fma_f32 v[0:1], v[42:43], v[78:79], v[0:1]
	v_mul_f32_e32 v5, v5, v6
	v_pk_fma_f32 v[0:1], v[48:49], v[86:87], v[0:1]
	v_cvt_pk_bf16_f32 v4, v4, v5
	v_lshlrev_b32_e32 v5, 16, v17
	v_mul_f32_e32 v0, v0, v5
	v_and_b32_e32 v5, 0xffff0000, v17
	v_mul_f32_e32 v1, v1, v5
	v_cvt_pk_bf16_f32 v5, v0, v1
	v_lshlrev_b64 v[0:1], 10, v[2:3]
	v_pk_mul_f32 v[2:3], v[68:69], v[80:81]
	v_lshl_add_u64 v[0:1], v[72:73], 0, v[0:1]
	v_pk_fma_f32 v[2:3], v[66:67], v[76:77], v[2:3]
	global_store_dwordx2 v[0:1], v[4:5], off nt
	v_pk_fma_f32 v[2:3], v[70:71], v[84:85], v[2:3]
	v_lshlrev_b32_e32 v4, 16, v14
	v_pk_mul_f32 v[0:1], v[48:49], v[82:83]
	v_mul_f32_e32 v2, v2, v4
	v_and_b32_e32 v4, 0xffff0000, v14
	v_pk_fma_f32 v[0:1], v[46:47], v[78:79], v[0:1]
	v_mul_f32_e32 v3, v3, v4
	v_pk_fma_f32 v[0:1], v[50:51], v[86:87], v[0:1]
	v_cvt_pk_bf16_f32 v2, v2, v3
	v_lshlrev_b32_e32 v3, 16, v15
	v_mul_f32_e32 v0, v0, v3
	v_and_b32_e32 v3, 0xffff0000, v15
	v_mul_f32_e32 v1, v1, v3
	s_mov_b32 s4, 0x3ffff
	v_cvt_pk_bf16_f32 v3, v0, v1
	v_lshlrev_b64 v[0:1], 10, v[12:13]
	v_cmp_lt_i32_e32 vcc, s4, v54
	v_lshl_add_u64 v[0:1], v[72:73], 0, v[0:1]
	s_or_b64 s[10:11], vcc, s[10:11]
	global_store_dwordx2 v[0:1], v[2:3], off nt
	s_andn2_b64 exec, exec, s[10:11]
	s_cbranch_execnz .LBB0_482
